# adaLN partial sums spread one layer per idle GEMM tail (layer-0, layer-1 and layer-2 scores phases), layer-1 rg weight transposes in the layer-2 scores tail
# speedup vs baseline: 1.1035x; 1.0016x over previous
; __device__ __forceinline__ float siluf_(float x) { return x / (1.0f + __expf(-x)); }
; __device__ __forceinline__ void phase_prologue(KP P, const Ctx& c) {
;     ...
;         for (int un = blockIdx.x; un < 4 * 24 * 8; un += gridDim.x) {
;             const int layer = un / 192, r = un % 192, nb = r / 8, kc = r % 8;
;             __syncthreads();
;             for (int i = c.tid; i < 5 * 256; i += 512) { const int v = i >> 8, k = kc * 256 + (i & 255); const float x = v < 4 ? P->in[I_C][v * D + k] : P->in[I_CCTX][k]; sl[i] = siluf_(x); }
;             __syncthreads();
;             const int cg = c.tid & 127, ks = c.tid >> 7;
;             const float* w = P->in[I_ADAW] + ((size_t)layer * D + kc * 256 + ks * 64) * 12288 + nb * 512 + cg * 4;
;             f32x4 a0 = (f32x4){0.f, 0.f, 0.f, 0.f}, a1 = a0, a2 = a0, a3 = a0, a4 = a0;
;             f32x4 wn[8];
; #pragma unroll
;             for (int i = 0; i < 8; ++i) wn[i] = *(const f32x4*)(w + (size_t)i * 12288);
.LBB0_1061:
	v_readlane_b32 s3, v244, 4
	s_cmpk_lg_i32 s3, 0x100
	s_cbranch_scc1 .Lj4a_skip
	s_cmp_lt_u32 s2, 32
	s_cbranch_scc1 .Lj4a_skip
	s_add_i32 s3, s2, 0xa0
	s_cmpk_gt_i32 s3, 0x17f
	s_cbranch_scc1 .Lj4a_skip
	v_writelane_b32 v240, s6, 0
	v_writelane_b32 v240, s7, 1
	v_writelane_b32 v240, s24, 2
	v_writelane_b32 v240, s25, 3
	v_writelane_b32 v240, s26, 4
	v_writelane_b32 v240, s27, 5
	v_writelane_b32 v240, s28, 6
	v_writelane_b32 v240, s29, 7
	v_writelane_b32 v240, s30, 8
	v_writelane_b32 v240, s31, 9
	v_writelane_b32 v240, s35, 10
	v_writelane_b32 v240, s36, 11
	v_writelane_b32 v240, s37, 12
	v_mov_b32_e32 v241, v1
	v_mov_b32_e32 v242, v96
	v_mov_b32_e32 v243, v97
	v_mov_b32_e32 v245, v98
	v_mov_b32_e32 v246, v99
	v_mov_b32_e32 v247, v101
	s_mov_b64 s[18:19], s[94:95]
	s_load_dwordx2 s[16:17], s[18:19], 0x130
	v_mov_b32_e32 v86, v0
	s_movk_i32 s3, 0xe0
	s_waitcnt vmcnt(0) lgkmcnt(0)
	s_barrier
	v_lshlrev_b32_e32 v1, 2, v86
	v_ashrrev_i32_e32 v3, 7, v86
	v_and_b32_e32 v2, 0x1fc, v1
	s_movk_i32 s6, 0x2700
	v_lshlrev_b32_e32 v88, 6, v3
	v_lshl_add_u32 v100, v3, 8, 0
	v_mul_lo_u32 v3, v3, s6
	v_lshlrev_b32_e32 v4, 2, v2
	v_add3_u32 v101, v100, v3, v4
	v_max_i32_e32 v3, 0x800, v86
	v_mov_b32_e32 v91, 0
	v_and_b32_e32 v90, 0x7fc, v1
	v_sub_u32_e32 v3, v3, v86
	s_waitcnt lgkmcnt(0)
	v_lshl_add_u64 v[4:5], s[16:17], 0, v[90:91]
	s_mov_b64 s[8:9], 0x200000
	v_add_u32_e32 v3, 0x1ff, v3
	s_load_dwordx2 s[20:21], s[18:19], 0x20
	v_lshl_add_u64 v[92:93], v[4:5], 0, s[8:9]
	v_lshrrev_b32_e32 v4, 9, v3
	s_movk_i32 s8, 0x1ff
	v_add_u32_e32 v5, 1, v4
	v_cmp_lt_u32_e64 s[8:9], s8, v3
	v_and_b32_e32 v3, 0xfffffe, v5
	v_add_u32_e32 v4, -1, v4
	v_lshl_add_u32 v102, v3, 9, v86
	v_cmp_ne_u32_e64 s[14:15], v5, v3
	v_and_b32_e32 v3, 0x7f, v86
	v_lshrrev_b32_e32 v6, 1, v4
	v_cmp_lt_u32_e64 s[10:11], 1, v4
	v_and_b32_e32 v4, 2, v4
	v_add_u32_e32 v104, 0, v90
	v_lshlrev_b32_e32 v90, 4, v3
	s_movk_i32 s4, 0x500
	s_movk_i32 s6, 0xa00
	v_add_u32_e32 v6, 1, v6
	v_cmp_eq_u32_e64 s[12:13], 0, v4
	v_add_u32_e32 v105, 0, v1
	s_waitcnt lgkmcnt(0)
	v_lshl_add_u64 v[4:5], s[20:21], 0, v[90:91]
	s_mov_b64 s[22:23], 0xb4000
	v_cmp_gt_i32_e64 s[4:5], s4, v86
	v_ashrrev_i32_e32 v89, 31, v88
	v_cmp_gt_i32_e64 s[6:7], s6, v86
	v_add_u32_e32 v87, 0x200, v86
	v_and_b32_e32 v103, -2, v6
	v_lshl_add_u64 v[94:95], v[4:5], 0, s[22:23]
	v_add_u32_e32 v106, 0x1400, v105
	s_movk_i32 s35, 0x2ff
	s_mov_b32 s36, 0xc000
	v_mov_b64_e32 v[96:97], s[20:21]
	v_lshlrev_b32_e32 v90, 2, v2
	s_mov_b32 s37, 0x18000
	s_mov_b32 s40, 0x24000
	s_mov_b32 s41, 0x30000
	s_mov_b32 s43, 0x3c000
	s_mov_b32 s44, 0x48000
	s_mov_b32 s45, 0x54000
	s_mov_b64 s[20:21], 0x60000
	s_movk_i32 s46, 0x7ff
	s_add_i32 s47, s2, 0xa0
	s_branch .Lj4a_8
.Lj4a_7:
	s_or_b64 exec, exec, s[26:27]
	s_add_i32 s47, s47, s3
	s_cmpk_gt_i32 s47, 0x17f
	s_cbranch_scc1 .Lj4a_done

; __device__ __forceinline__ void phase_modfin(KP P, const Ctx& c) {
;     for (int i = c.gtid; i < 4 * 5 * 12288; i += c.ngt) { const int n = i % 12288, lv = i / 12288, l = lv / 5, v = lv % 5;
;         float s = P->in[I_ADAB][l * 12288 + n];
;         for (int kc = 0; kc < 8; ++kc) s += ((const float*)(P->ws + WS_MODP))[((size_t)(l * 8 + kc) * 5 + v) * 12288 + n];
;         ((float*)(P->ws + WS_MOD))[i] = s; }
.LBB0_1113:
	s_or_b64 exec, exec, s[38:39]
	s_mov_b64 s[0:1], s[94:95]
	s_waitcnt lgkmcnt(0)
	v_mov_b32_e32 v2, v0
	s_barrier
	v_readlane_b32 s3, v244, 4
	s_cmpk_lg_i32 s3, 0x100
	s_cbranch_scc1 .Lmfa_done
	s_load_dwordx2 s[8:9], s[94:95], 0x28
	s_load_dwordx2 s[10:11], s[94:95], 0x130
	v_lshl_add_u32 v3, s2, 9, v0
	v_add_u32_e32 v3, 0xf000, v3
	v_mov_b32_e32 v4, 0x1e000
	v_cmp_lt_u32_e64 s[14:15], v3, v4
	s_and_saveexec_b64 s[12:13], s[14:15]
	s_cbranch_execz .Lmfa_end
	v_lshrrev_b32_e32 v4, 12, v3
	v_mul_u32_u24_e32 v4, 0xaaab, v4
	v_lshrrev_b32_e32 v4, 17, v4
	v_mul_u32_u24_e32 v5, 0x3000, v4
	v_sub_u32_e32 v5, v3, v5
	v_mul_u32_u24_e32 v6, 0x3334, v4
	v_lshrrev_b32_e32 v6, 16, v6
	v_mul_u32_u24_e32 v7, 5, v6
	v_sub_u32_e32 v7, v4, v7
	v_mul_u32_u24_e32 v8, 0x3000, v6
	v_add_lshl_u32 v8, v8, v5, 2
	v_mul_u32_u24_e32 v9, 40, v6
	v_add_u32_e32 v9, v9, v7
	v_mul_u32_u24_e32 v9, 0x3000, v9
	v_add_lshl_u32 v9, v9, v5, 2
	v_add_u32_e32 v9, 0x200000, v9
	v_lshlrev_b32_e32 v10, 2, v3
	v_add_u32_e32 v10, 0xa00000, v10
	s_waitcnt lgkmcnt(0)
	global_load_dword v11, v8, s[8:9]
	global_load_dword v12, v9, s[10:11]
	v_add_u32_e32 v9, 0x3c000, v9
	global_load_dword v13, v9, s[10:11]
	v_add_u32_e32 v9, 0x3c000, v9
	global_load_dword v14, v9, s[10:11]
	v_add_u32_e32 v9, 0x3c000, v9
	global_load_dword v15, v9, s[10:11]
	v_add_u32_e32 v9, 0x3c000, v9
	global_load_dword v16, v9, s[10:11]
	v_add_u32_e32 v9, 0x3c000, v9
	global_load_dword v17, v9, s[10:11]
	v_add_u32_e32 v9, 0x3c000, v9
	global_load_dword v18, v9, s[10:11]
	v_add_u32_e32 v9, 0x3c000, v9
	global_load_dword v19, v9, s[10:11]
	s_waitcnt vmcnt(7)
	v_add_f32_e32 v11, v11, v12
	s_waitcnt vmcnt(6)
	v_add_f32_e32 v11, v11, v13
	s_waitcnt vmcnt(5)
	v_add_f32_e32 v11, v11, v14
	s_waitcnt vmcnt(4)
	v_add_f32_e32 v11, v11, v15
	s_waitcnt vmcnt(3)
	v_add_f32_e32 v11, v11, v16
	s_waitcnt vmcnt(2)
	v_add_f32_e32 v11, v11, v17
	s_waitcnt vmcnt(1)
	v_add_f32_e32 v11, v11, v18
	s_waitcnt vmcnt(0)
	v_add_f32_e32 v11, v11, v19
	global_store_dword v10, v11, s[10:11]

; __device__ __forceinline__ float siluf_(float x) { return x / (1.0f + __expf(-x)); }
; __device__ __forceinline__ void phase_prologue(KP P, const Ctx& c) {
;     ...
;         for (int un = blockIdx.x; un < 4 * 24 * 8; un += gridDim.x) {
;             const int layer = un / 192, r = un % 192, nb = r / 8, kc = r % 8;
;             __syncthreads();
;             for (int i = c.tid; i < 5 * 256; i += 512) { const int v = i >> 8, k = kc * 256 + (i & 255); const float x = v < 4 ? P->in[I_C][v * D + k] : P->in[I_CCTX][k]; sl[i] = siluf_(x); }
;             __syncthreads();
;             const int cg = c.tid & 127, ks = c.tid >> 7;
;             const float* w = P->in[I_ADAW] + ((size_t)layer * D + kc * 256 + ks * 64) * 12288 + nb * 512 + cg * 4;
;             f32x4 a0 = (f32x4){0.f, 0.f, 0.f, 0.f}, a1 = a0, a2 = a0, a3 = a0, a4 = a0;
;             f32x4 wn[8];
; #pragma unroll
;             for (int i = 0; i < 8; ++i) wn[i] = *(const f32x4*)(w + (size_t)i * 12288);
.LBB0_2043:
	v_readlane_b32 s3, v244, 4
	s_cmpk_lg_i32 s3, 0x100
	s_cbranch_scc1 .Lj4b_skip
	s_cmp_lt_u32 s2, 32
	s_cbranch_scc1 .Lj4b_skip
	s_add_i32 s3, s2, 0x160
	s_cmpk_gt_i32 s3, 0x23f
	s_cbranch_scc1 .Lj4b_skip
	v_writelane_b32 v240, s6, 0
	v_writelane_b32 v240, s7, 1
	v_writelane_b32 v240, s24, 2
	v_writelane_b32 v240, s25, 3
	v_writelane_b32 v240, s26, 4
	v_writelane_b32 v240, s27, 5
	v_writelane_b32 v240, s28, 6
	v_writelane_b32 v240, s29, 7
	v_writelane_b32 v240, s30, 8
	v_writelane_b32 v240, s31, 9
	v_writelane_b32 v240, s35, 10
	v_writelane_b32 v240, s36, 11
	v_writelane_b32 v240, s37, 12
	v_mov_b32_e32 v241, v1
	s_mov_b64 s[18:19], s[94:95]
	s_load_dwordx2 s[16:17], s[18:19], 0x130
	v_mov_b32_e32 v86, v0
	s_movk_i32 s3, 0xe0
	s_waitcnt vmcnt(0) lgkmcnt(0)
	s_barrier
	v_lshlrev_b32_e32 v1, 2, v86
	v_ashrrev_i32_e32 v3, 7, v86
	v_and_b32_e32 v2, 0x1fc, v1
	s_movk_i32 s6, 0x2700
	v_lshlrev_b32_e32 v88, 6, v3
	v_lshl_add_u32 v100, v3, 8, 0
	v_mul_lo_u32 v3, v3, s6
	v_lshlrev_b32_e32 v4, 2, v2
	v_add3_u32 v101, v100, v3, v4
	v_max_i32_e32 v3, 0x800, v86
	v_mov_b32_e32 v91, 0
	v_and_b32_e32 v90, 0x7fc, v1
	v_sub_u32_e32 v3, v3, v86
	s_waitcnt lgkmcnt(0)
	v_lshl_add_u64 v[4:5], s[16:17], 0, v[90:91]
	s_mov_b64 s[8:9], 0x200000
	v_add_u32_e32 v3, 0x1ff, v3
	s_load_dwordx2 s[20:21], s[18:19], 0x20
	v_lshl_add_u64 v[92:93], v[4:5], 0, s[8:9]
	v_lshrrev_b32_e32 v4, 9, v3
	s_movk_i32 s8, 0x1ff
	v_add_u32_e32 v5, 1, v4
	v_cmp_lt_u32_e64 s[8:9], s8, v3
	v_and_b32_e32 v3, 0xfffffe, v5
	v_add_u32_e32 v4, -1, v4
	v_lshl_add_u32 v102, v3, 9, v86
	v_cmp_ne_u32_e64 s[14:15], v5, v3
	v_and_b32_e32 v3, 0x7f, v86
	v_lshrrev_b32_e32 v6, 1, v4
	v_cmp_lt_u32_e64 s[10:11], 1, v4
	v_and_b32_e32 v4, 2, v4
	v_add_u32_e32 v104, 0, v90
	v_lshlrev_b32_e32 v90, 4, v3
	s_movk_i32 s4, 0x500
	s_movk_i32 s6, 0xa00
	v_add_u32_e32 v6, 1, v6
	v_cmp_eq_u32_e64 s[12:13], 0, v4
	v_add_u32_e32 v105, 0, v1
	s_waitcnt lgkmcnt(0)
	v_lshl_add_u64 v[4:5], s[20:21], 0, v[90:91]
	s_mov_b64 s[22:23], 0xb4000
	v_cmp_gt_i32_e64 s[4:5], s4, v86
	v_ashrrev_i32_e32 v89, 31, v88
	v_cmp_gt_i32_e64 s[6:7], s6, v86
	v_add_u32_e32 v87, 0x200, v86
	v_and_b32_e32 v103, -2, v6
	v_lshl_add_u64 v[94:95], v[4:5], 0, s[22:23]
	v_add_u32_e32 v106, 0x1400, v105
	s_movk_i32 s35, 0x2ff
	s_mov_b32 s36, 0xc000
	v_mov_b64_e32 v[96:97], s[20:21]
	v_lshlrev_b32_e32 v90, 2, v2
	s_mov_b32 s37, 0x18000
	s_mov_b32 s40, 0x24000
	s_mov_b32 s41, 0x30000
	s_mov_b32 s43, 0x3c000
	s_mov_b32 s44, 0x48000
	s_mov_b32 s45, 0x54000
	s_mov_b64 s[20:21], 0x60000
	s_movk_i32 s46, 0x7ff
	s_add_i32 s47, s2, 0x160
	s_branch .Lj4b_8

; __device__ __forceinline__ void phase_modfin(KP P, const Ctx& c) {
;     for (int i = c.gtid; i < 4 * 5 * 12288; i += c.ngt) { const int n = i % 12288, lv = i / 12288, l = lv / 5, v = lv % 5;
;         float s = P->in[I_ADAB][l * 12288 + n];
;         for (int kc = 0; kc < 8; ++kc) s += ((const float*)(P->ws + WS_MODP))[((size_t)(l * 8 + kc) * 5 + v) * 12288 + n];
;         ((float*)(P->ws + WS_MOD))[i] = s; }
.LBB0_2095:
	s_or_b64 exec, exec, s[38:39]
	s_mov_b64 s[0:1], s[94:95]
	s_waitcnt lgkmcnt(0)
	v_mov_b32_e32 v2, v0
	s_barrier
	v_readlane_b32 s3, v244, 4
	s_cmpk_lg_i32 s3, 0x100
	s_cbranch_scc1 .Lmfb_done
	s_load_dwordx2 s[8:9], s[94:95], 0x28
	s_load_dwordx2 s[10:11], s[94:95], 0x130
	v_lshl_add_u32 v3, s2, 9, v0
	v_add_u32_e32 v3, 0x1e000, v3
	v_mov_b32_e32 v4, 0x2d000
	v_cmp_lt_u32_e64 s[14:15], v3, v4
	s_and_saveexec_b64 s[12:13], s[14:15]
	s_cbranch_execz .Lmfb_end
	v_lshrrev_b32_e32 v4, 12, v3
	v_mul_u32_u24_e32 v4, 0xaaab, v4
	v_lshrrev_b32_e32 v4, 17, v4
	v_mul_u32_u24_e32 v5, 0x3000, v4
	v_sub_u32_e32 v5, v3, v5
	v_mul_u32_u24_e32 v6, 0x3334, v4
	v_lshrrev_b32_e32 v6, 16, v6
	v_mul_u32_u24_e32 v7, 5, v6
	v_sub_u32_e32 v7, v4, v7
	v_mul_u32_u24_e32 v8, 0x3000, v6
	v_add_lshl_u32 v8, v8, v5, 2
	v_mul_u32_u24_e32 v9, 40, v6
	v_add_u32_e32 v9, v9, v7
	v_mul_u32_u24_e32 v9, 0x3000, v9
	v_add_lshl_u32 v9, v9, v5, 2
	v_add_u32_e32 v9, 0x200000, v9
	v_lshlrev_b32_e32 v10, 2, v3
	v_add_u32_e32 v10, 0xa00000, v10
	s_waitcnt lgkmcnt(0)
	global_load_dword v11, v8, s[8:9]
	global_load_dword v12, v9, s[10:11]
	v_add_u32_e32 v9, 0x3c000, v9
	global_load_dword v13, v9, s[10:11]
	v_add_u32_e32 v9, 0x3c000, v9
	global_load_dword v14, v9, s[10:11]
	v_add_u32_e32 v9, 0x3c000, v9
	global_load_dword v15, v9, s[10:11]
	v_add_u32_e32 v9, 0x3c000, v9
	global_load_dword v16, v9, s[10:11]
	v_add_u32_e32 v9, 0x3c000, v9
	global_load_dword v17, v9, s[10:11]
	v_add_u32_e32 v9, 0x3c000, v9
	global_load_dword v18, v9, s[10:11]
	v_add_u32_e32 v9, 0x3c000, v9
	global_load_dword v19, v9, s[10:11]
	s_waitcnt vmcnt(7)
	v_add_f32_e32 v11, v11, v12
	s_waitcnt vmcnt(6)
	v_add_f32_e32 v11, v11, v13
	s_waitcnt vmcnt(5)
	v_add_f32_e32 v11, v11, v14
	s_waitcnt vmcnt(4)
	v_add_f32_e32 v11, v11, v15
	s_waitcnt vmcnt(3)
	v_add_f32_e32 v11, v11, v16
	s_waitcnt vmcnt(2)
	v_add_f32_e32 v11, v11, v17
	s_waitcnt vmcnt(1)
	v_add_f32_e32 v11, v11, v18
	s_waitcnt vmcnt(0)
	v_add_f32_e32 v11, v11, v19
	global_store_dword v10, v11, s[10:11]

; __device__ __forceinline__ float siluf_(float x) { return x / (1.0f + __expf(-x)); }
; __device__ __forceinline__ void phase_prologue(KP P, const Ctx& c) {
;     ...
;         for (int un = blockIdx.x; un < 4 * 24 * 8; un += gridDim.x) {
;             const int layer = un / 192, r = un % 192, nb = r / 8, kc = r % 8;
;             __syncthreads();
;             for (int i = c.tid; i < 5 * 256; i += 512) { const int v = i >> 8, k = kc * 256 + (i & 255); const float x = v < 4 ? P->in[I_C][v * D + k] : P->in[I_CCTX][k]; sl[i] = siluf_(x); }
;             __syncthreads();
;             const int cg = c.tid & 127, ks = c.tid >> 7;
;             const float* w = P->in[I_ADAW] + ((size_t)layer * D + kc * 256 + ks * 64) * 12288 + nb * 512 + cg * 4;
;             f32x4 a0 = (f32x4){0.f, 0.f, 0.f, 0.f}, a1 = a0, a2 = a0, a3 = a0, a4 = a0;
;             f32x4 wn[8];
; #pragma unroll
;             for (int i = 0; i < 8; ++i) wn[i] = *(const f32x4*)(w + (size_t)i * 12288);
.LBB0_2849:
	v_readlane_b32 s3, v244, 4
	s_cmpk_lg_i32 s3, 0x100
	s_cbranch_scc1 .Lj4c_skip
	s_cmp_lt_u32 s2, 32
	s_cbranch_scc1 .Lj4c_skip
	s_add_i32 s3, s2, 0x220
	s_cmpk_gt_i32 s3, 0x2ff
	s_cbranch_scc1 .Lj4c_skip
	v_writelane_b32 v240, s6, 0
	v_writelane_b32 v240, s7, 1
	v_writelane_b32 v240, s24, 2
	v_writelane_b32 v240, s26, 3
	v_writelane_b32 v240, s27, 4
	v_writelane_b32 v240, s28, 5
	v_writelane_b32 v240, s29, 6
	v_writelane_b32 v240, s30, 7
	v_writelane_b32 v240, s31, 8
	v_writelane_b32 v240, s35, 9
	v_writelane_b32 v240, s36, 10
	v_writelane_b32 v240, s37, 11
	v_mov_b32_e32 v241, v1
	s_mov_b64 s[18:19], s[94:95]
	s_load_dwordx2 s[16:17], s[18:19], 0x130
	v_mov_b32_e32 v86, v0
	s_movk_i32 s3, 0xe0
	s_waitcnt vmcnt(0) lgkmcnt(0)
	s_barrier
	v_lshlrev_b32_e32 v1, 2, v86
	v_ashrrev_i32_e32 v3, 7, v86
	v_and_b32_e32 v2, 0x1fc, v1
	s_movk_i32 s6, 0x2700
	v_lshlrev_b32_e32 v88, 6, v3
	v_lshl_add_u32 v100, v3, 8, 0
	v_mul_lo_u32 v3, v3, s6
	v_lshlrev_b32_e32 v4, 2, v2
	v_add3_u32 v101, v100, v3, v4
	v_max_i32_e32 v3, 0x800, v86
	v_mov_b32_e32 v91, 0
	v_and_b32_e32 v90, 0x7fc, v1
	v_sub_u32_e32 v3, v3, v86
	s_waitcnt lgkmcnt(0)
	v_lshl_add_u64 v[4:5], s[16:17], 0, v[90:91]
	s_mov_b64 s[8:9], 0x200000
	v_add_u32_e32 v3, 0x1ff, v3
	s_load_dwordx2 s[20:21], s[18:19], 0x20
	v_lshl_add_u64 v[92:93], v[4:5], 0, s[8:9]
	v_lshrrev_b32_e32 v4, 9, v3
	s_movk_i32 s8, 0x1ff
	v_add_u32_e32 v5, 1, v4
	v_cmp_lt_u32_e64 s[8:9], s8, v3
	v_and_b32_e32 v3, 0xfffffe, v5
	v_add_u32_e32 v4, -1, v4
	v_lshl_add_u32 v102, v3, 9, v86
	v_cmp_ne_u32_e64 s[14:15], v5, v3
	v_and_b32_e32 v3, 0x7f, v86
	v_lshrrev_b32_e32 v6, 1, v4
	v_cmp_lt_u32_e64 s[10:11], 1, v4
	v_and_b32_e32 v4, 2, v4
	v_add_u32_e32 v104, 0, v90
	v_lshlrev_b32_e32 v90, 4, v3
	s_movk_i32 s4, 0x500
	s_movk_i32 s6, 0xa00
	v_add_u32_e32 v6, 1, v6
	v_cmp_eq_u32_e64 s[12:13], 0, v4
	v_add_u32_e32 v105, 0, v1
	s_waitcnt lgkmcnt(0)
	v_lshl_add_u64 v[4:5], s[20:21], 0, v[90:91]
	s_mov_b64 s[22:23], 0xb4000
	v_cmp_gt_i32_e64 s[4:5], s4, v86
	v_ashrrev_i32_e32 v89, 31, v88
	v_cmp_gt_i32_e64 s[6:7], s6, v86
	v_add_u32_e32 v87, 0x200, v86
	v_and_b32_e32 v103, -2, v6
	v_lshl_add_u64 v[94:95], v[4:5], 0, s[22:23]
	v_add_u32_e32 v106, 0x1400, v105
	s_movk_i32 s35, 0x2ff
	s_mov_b32 s36, 0xc000
	v_mov_b64_e32 v[96:97], s[20:21]
	v_lshlrev_b32_e32 v90, 2, v2
	s_mov_b32 s37, 0x18000
	s_mov_b32 s40, 0x24000
	s_mov_b32 s41, 0x30000
	s_mov_b32 s43, 0x3c000
	s_mov_b32 s44, 0x48000
	s_mov_b32 s45, 0x54000
	s_mov_b64 s[20:21], 0x60000
	s_movk_i32 s46, 0x7ff
	s_add_i32 s47, s2, 0x220
	s_branch .Lj4c_8

; __device__ __forceinline__ void phase_prologue(KP P, const Ctx& c) {
;     ...
;         }
;         __syncthreads();
;     }
.Lj4c_done:
	s_waitcnt vmcnt(0) lgkmcnt(0)
	s_barrier
	v_readlane_b32 s6, v240, 0
	v_readlane_b32 s7, v240, 1
	v_readlane_b32 s24, v240, 2
	v_readlane_b32 s26, v240, 3
	v_readlane_b32 s27, v240, 4
	v_readlane_b32 s28, v240, 5
	v_readlane_b32 s29, v240, 6
	v_readlane_b32 s30, v240, 7
	v_readlane_b32 s31, v240, 8
	v_readlane_b32 s35, v240, 9
	v_readlane_b32 s36, v240, 10
	v_readlane_b32 s37, v240, 11
	v_mov_b32_e32 v1, v241

; #define SEL_LOAD(k) do { const int pid_ = 2 * row_lo + c.gw + (k) * c.ngw; const float* sp_ = S + (size_t)(pid_ >> 1) * D + (2 * (pid_ & 1)) * 512 + lane * 8; \
;         sn[0][0] = *(const f32x4*)sp_; sn[0][1] = *(const f32x4*)(sp_ + 4); sn[1][0] = *(const f32x4*)(sp_ + 512); sn[1][1] = *(const f32x4*)(sp_ + 516); } while (0)
; __device__ __forceinline__ void phase_peer_select(KP P, const Ctx& c, int row_lo) {
;     const float* S = (const float*)(P->ws + WS_S); float* SW = (float*)(P->ws + WS_SELW);
;     constexpr int KMIN = (int)0x80000000;
;     const int nps = (2 * (T - row_lo) - c.gw + c.ngw - 1) / c.ngw;
;     f32x4 sn[2][2];
;     ...
;     { int lane = c.lane; asm volatile("" : "+v"(lane)); if (nps > 0) SEL_LOAD(0); }
.Lmfc_done:
	s_load_dwordx2 s[38:39], s[0:1], 0x130
	v_readfirstlane_b32 s0, v2
	s_ashr_i32 s0, s0, 6
	v_readlane_b32 s1, v239, 11
	s_add_i32 s3, s0, s1
	s_waitcnt lgkmcnt(0)
	s_add_u32 s1, s38, 0x45400000
	v_readlane_b32 s4, v239, 27
	s_addc_u32 s8, s39, 0
	s_sub_i32 s4, s4, s3
	s_ashr_i32 s5, s4, 31
	s_abs_i32 s4, s4
	v_readlane_b32 s9, v239, 30
	v_readlane_b32 s10, v239, 28
	s_mul_hi_u32 s9, s4, s9
	v_readlane_b32 s12, v239, 31
	s_mul_i32 s10, s9, s12
	v_readlane_b32 s11, v239, 29
	s_sub_i32 s4, s4, s10
	s_xor_b32 s5, s5, s11
	s_add_i32 s10, s9, 1
	s_sub_i32 s11, s4, s12
	s_cmp_ge_u32 s4, s12
	s_cselect_b32 s9, s10, s9
	s_cselect_b32 s4, s11, s4
	s_add_i32 s10, s9, 1
	s_cmp_ge_u32 s4, s12
	s_cselect_b32 s4, s10, s9
	s_xor_b32 s4, s4, s5
	s_sub_i32 s4, s4, s5
	v_and_b32_e32 v34, 63, v2
	s_cmp_gt_i32 s4, 0
	v_mov_b32_e32 v2, v34
	s_cselect_b64 s[40:41], -1, 0
	s_cmp_lt_i32 s4, 1
	s_cbranch_scc1 .LBB0_2903
	s_ashr_i32 s10, s3, 1
	s_ashr_i32 s11, s10, 31
	s_lshl_b64 s[10:11], s[10:11], 13
	s_add_u32 s5, s1, s10
	s_addc_u32 s9, s8, s11
	s_lshl_b32 s10, s0, 12
	s_and_b32 s10, s10, 0x1000
	s_add_u32 s10, s5, s10
	v_lshlrev_b32_e32 v2, 3, v2
	s_addc_u32 s11, s9, 0
	v_ashrrev_i32_e32 v3, 31, v2
	v_lshl_add_u64 v[2:3], v[2:3], 2, s[10:11]
	global_load_dwordx4 v[26:29], v[2:3], off offset:16
	global_load_dwordx4 v[30:33], v[2:3], off
	global_load_dwordx4 v[18:21], v[2:3], off offset:2064
	global_load_dwordx4 v[22:25], v[2:3], off offset:2048
	s_andn2_b64 vcc, exec, s[40:41]
	s_cbranch_vccz .LBB0_2904
	s_branch .LBB0_2968
